# code placement: gemm main loop head padded to a 64-byte boundary
# speedup vs baseline: 1.0439x; 1.0005x over previous
; #define STAGE8(Q, BASE, br, kt) do { const bf16_t* sb_ = (BASE) + ((long)(br) * K + (long)(kt) * BK8); \
;     _Pragma("unroll") for (int i_ = 0; i_ < 2; ++i_) \
;       __builtin_amdgcn_global_load_lds((const unsigned*)(sb_ + goff[i_]), (unsigned*)(smem + (Q) * HTB + i_ * 8192 + wu8 * 1024), 16, 0, 0); } while (0)
; #define WAIT_V8(n) asm volatile("s_waitcnt vmcnt(" #n ")" ::: "memory")
; #define BAR8 __builtin_amdgcn_s_barrier()
; DI void gemm8p(const bf16_t* __restrict__ A, const bf16_t* __restrict__ Bt, int K, f32x4v (&acc)[2][2][4][2], char* smem) {
;     ...
; #pragma unroll
;   for (int a = 0; a < 2; ++a)
; #pragma unroll
;     for (int b = 0; b < 2; ++b)
; #pragma unroll
;       for (int m = 0; m < 4; ++m)
; #pragma unroll
;         for (int n = 0; n < 2; ++n) acc[a][b][m][n] = f32x4v{0.f, 0.f, 0.f, 0.f};
;   bf16x8 At[4][2], B0[2][2], B1[2][2];
;   const int nt = K / BK8;
;   asm volatile("s_waitcnt vmcnt(0)" ::: "memory");
;   __syncthreads();
;   STAGE8(SB8(0, 0), Bt, 0, 0); STAGE8(SA8(0, 0), A, 0, 0);
;   STAGE8(SB8(0, 1), Bt, HALF8, 0); STAGE8(SA8(0, 1), A, HALF8, 0);
;   if (wr == 1) BAR8;
;   WAIT_V8(4); BAR8;
;   STAGE8(SB8(1, 0), Bt, 0, 1); STAGE8(SA8(1, 0), A, 0, 1); STAGE8(SB8(1, 1), Bt, HALF8, 1);
;   WAIT_V8(6); BAR8;
.LBB0_463:
	s_or_b64 exec, exec, s[8:9]
	s_xor_b64 s[6:7], s[6:7], -1
	v_writelane_b32 v250, s6, 12
	v_lshl_add_u64 v[2:3], v[2:3], 0, s[92:93]
	s_waitcnt vmcnt(4)
	s_barrier
	v_writelane_b32 v250, s7, 13
	s_add_i32 s6, s10, 0x18000
	s_mov_b32 m0, s6
	s_add_i32 s7, s10, 0x1a000
	global_load_lds_dwordx4 v[2:3], off
	v_lshl_add_u64 v[2:3], v[4:5], 0, s[92:93]
	s_mov_b32 m0, s7
	s_add_i32 s8, s10, 0x8000
	global_load_lds_dwordx4 v[2:3], off
	v_lshl_add_u64 v[2:3], v[8:9], 0, s[92:93]
	s_mov_b32 m0, s8
	s_add_i32 s9, s10, 0xa000
	global_load_lds_dwordx4 v[2:3], off
	v_lshl_add_u64 v[2:3], v[6:7], 0, s[92:93]
	s_mov_b32 m0, s9
	s_add_i32 s30, s10, 0x1c000
	global_load_lds_dwordx4 v[2:3], off
	v_lshl_add_u64 v[2:3], v[10:11], 0, s[92:93]
	s_mov_b32 m0, s30
	s_add_i32 s31, s10, 0x1e000
	global_load_lds_dwordx4 v[2:3], off
	v_lshl_add_u64 v[2:3], v[12:13], 0, s[92:93]
	s_mov_b32 m0, s31
	s_xor_b64 s[4:5], s[4:5], -1
	global_load_lds_dwordx4 v[2:3], off
	v_and_b32_e32 v23, 15, v148
	v_lshlrev_b32_e32 v24, 2, v148
	v_lshlrev_b32_e32 v21, 12, v21
	s_waitcnt vmcnt(6)
	v_add3_u32 v2, v20, v18, v19
	v_mov_b32_e32 v3, v1
	v_add3_u32 v4, v16, v14, v15
	v_mov_b32_e32 v5, v1
	v_writelane_b32 v250, s4, 14
	v_and_b32_e32 v22, 48, v148
	v_lshlrev_b32_e32 v23, 6, v23
	v_and_b32_e32 v24, 32, v24
	v_and_b32_e32 v21, 0x3000, v21
	v_lshlrev_b64 v[2:3], 1, v[2:3]
	v_lshlrev_b64 v[4:5], 1, v[4:5]
	s_lshl_b64 s[52:53], s[80:81], 8
	v_writelane_b32 v250, s5, 15
	v_lshlrev_b32_e32 v17, 13, v17
	v_or_b32_e32 v21, 0x10000, v21
	v_bitop3_b32 v22, v23, v24, v22 bitop3:0x36
	s_lshr_b32 s5, s80, 6
	v_lshl_add_u64 v[132:133], s[0:1], 0, v[2:3]
	v_lshl_add_u64 v[6:7], s[52:53], 0, v[2:3]
	v_lshl_add_u64 v[8:9], s[52:53], 0, v[4:5]
	v_lshl_add_u64 v[140:141], s[2:3], 0, v[2:3]
	v_mov_b32_e32 v2, 0
	s_lshl_b32 s4, s80, 7
	s_barrier
	s_add_i32 s35, s5, -2
	v_lshl_add_u64 v[134:135], s[0:1], 0, v[4:5]
	v_lshl_add_u64 v[136:137], s[2:3], 0, v[6:7]
	v_lshl_add_u64 v[138:139], s[2:3], 0, v[8:9]
	v_lshl_add_u64 v[142:143], s[2:3], 0, v[4:5]
	v_lshl_add_u64 v[144:145], s[0:1], 0, v[8:9]
	v_lshl_add_u64 v[146:147], s[0:1], 0, v[6:7]
	s_mov_b32 s52, 0
	s_mov_b64 s[2:3], 0
	s_add_i32 s34, s10, 0xe000
	v_add_u32_e32 v150, v21, v22
	v_add_u32_e32 v149, v17, v22
	v_mov_b32_e32 v3, v2
	v_mov_b32_e32 v4, v2
	v_mov_b32_e32 v5, v2
	v_mov_b32_e32 v6, v2
	v_mov_b32_e32 v7, v2
	v_mov_b32_e32 v8, v2
	v_mov_b32_e32 v9, v2
	v_mov_b32_e32 v10, v2
	v_mov_b32_e32 v11, v2
	v_mov_b32_e32 v12, v2
	v_mov_b32_e32 v13, v2
	v_mov_b32_e32 v14, v2
	v_mov_b32_e32 v15, v2
	v_mov_b32_e32 v16, v2
	v_mov_b32_e32 v17, v2
	v_mov_b32_e32 v18, v2
	v_mov_b32_e32 v19, v2
	v_mov_b32_e32 v20, v2
	v_mov_b32_e32 v21, v2
	v_mov_b32_e32 v22, v2
	v_mov_b32_e32 v23, v2
	v_mov_b32_e32 v24, v2
	v_mov_b32_e32 v25, v2
	v_mov_b32_e32 v26, v2
	v_mov_b32_e32 v27, v2
	v_mov_b32_e32 v28, v2
	v_mov_b32_e32 v29, v2
	v_mov_b32_e32 v30, v2
	v_mov_b32_e32 v31, v2
	v_mov_b32_e32 v32, v2
	v_mov_b32_e32 v33, v2
	v_mov_b32_e32 v34, v2
	v_mov_b32_e32 v35, v2
	v_mov_b32_e32 v36, v2
	v_mov_b32_e32 v37, v2
	v_mov_b32_e32 v38, v2
	v_mov_b32_e32 v39, v2
	v_mov_b32_e32 v40, v2
	v_mov_b32_e32 v41, v2
	v_mov_b32_e32 v42, v2
	v_mov_b32_e32 v43, v2
	v_mov_b32_e32 v44, v2
	v_mov_b32_e32 v45, v2
	v_mov_b32_e32 v46, v2
	v_mov_b32_e32 v47, v2
	v_mov_b32_e32 v48, v2
	v_mov_b32_e32 v49, v2
	v_mov_b32_e32 v50, v2
	v_mov_b32_e32 v51, v2
	v_mov_b32_e32 v52, v2
	v_mov_b32_e32 v53, v2
	v_mov_b32_e32 v54, v2
	v_mov_b32_e32 v55, v2
	v_mov_b32_e32 v56, v2
	v_mov_b32_e32 v57, v2
	v_mov_b32_e32 v58, v2
	v_mov_b32_e32 v59, v2
	v_mov_b32_e32 v60, v2
	v_mov_b32_e32 v61, v2
	v_mov_b32_e32 v62, v2
	v_mov_b32_e32 v63, v2
	v_mov_b32_e32 v64, v2
	v_mov_b32_e32 v65, v2
	v_mov_b32_e32 v66, v2
	v_mov_b32_e32 v67, v2
	v_mov_b32_e32 v68, v2
	v_mov_b32_e32 v69, v2
	v_mov_b32_e32 v70, v2
	v_mov_b32_e32 v71, v2
	v_mov_b32_e32 v72, v2
	v_mov_b32_e32 v73, v2
	v_mov_b32_e32 v74, v2
	v_mov_b32_e32 v75, v2
	v_mov_b32_e32 v76, v2
	v_mov_b32_e32 v77, v2
	v_mov_b32_e32 v78, v2
	v_mov_b32_e32 v79, v2
	v_mov_b32_e32 v80, v2
	v_mov_b32_e32 v81, v2
	v_mov_b32_e32 v82, v2
	v_mov_b32_e32 v83, v2
	v_mov_b32_e32 v84, v2
	v_mov_b32_e32 v85, v2
	v_mov_b32_e32 v86, v2
	v_mov_b32_e32 v87, v2
	v_mov_b32_e32 v88, v2
	v_mov_b32_e32 v89, v2
	v_mov_b32_e32 v90, v2
	v_mov_b32_e32 v91, v2
	v_mov_b32_e32 v92, v2
	v_mov_b32_e32 v93, v2
	v_mov_b32_e32 v94, v2
	v_mov_b32_e32 v95, v2
	v_mov_b32_e32 v96, v2
	v_mov_b32_e32 v97, v2
	v_mov_b32_e32 v98, v2
	v_mov_b32_e32 v99, v2
	v_mov_b32_e32 v100, v2
	v_mov_b32_e32 v101, v2
	v_mov_b32_e32 v102, v2
	v_mov_b32_e32 v103, v2
	v_mov_b32_e32 v104, v2
	v_mov_b32_e32 v105, v2
	v_mov_b32_e32 v106, v2
	v_mov_b32_e32 v107, v2
	v_mov_b32_e32 v108, v2
	v_mov_b32_e32 v109, v2
	v_mov_b32_e32 v110, v2
	v_mov_b32_e32 v111, v2
	v_mov_b32_e32 v112, v2
	v_mov_b32_e32 v113, v2
	v_mov_b32_e32 v114, v2
	v_mov_b32_e32 v115, v2
	v_mov_b32_e32 v116, v2
	v_mov_b32_e32 v117, v2
	v_mov_b32_e32 v118, v2
	v_mov_b32_e32 v119, v2
	v_mov_b32_e32 v120, v2
	v_mov_b32_e32 v121, v2
	v_mov_b32_e32 v122, v2
	v_mov_b32_e32 v123, v2
	v_mov_b32_e32 v124, v2
	v_mov_b32_e32 v125, v2
	v_mov_b32_e32 v126, v2
	v_mov_b32_e32 v127, v2
	v_mov_b32_e32 v128, v2
	v_mov_b32_e32 v129, v2
	s_nop 0
	s_nop 0
	s_nop 0
	s_nop 0
	s_nop 0
	s_nop 0
	s_nop 0
	s_nop 0
	s_nop 0
	s_nop 0
	s_nop 0
	s_nop 0
	s_nop 0
